# LN1/LN2 affine gain/bias vector loads batched in the row-norm passes
# speedup vs baseline: 1.0426x; 1.0034x over previous
.LBB0_1565:
	s_or_b64 exec, exec, s[4:5]
	s_add_u32 s4, s16, s2
	s_addc_u32 s5, s17, s3
	s_add_u32 s14, s14, s2
	v_lshlrev_b64 v[36:37], 2, v[34:35]
	s_addc_u32 s15, s15, s3
	v_lshl_add_u64 v[44:45], s[4:5], 0, v[36:37]
	v_lshl_add_u64 v[46:47], s[14:15], 0, v[36:37]
	v_add_co_u32_e32 v60, vcc, s71, v44
	s_nop 1
	v_addc_co_u32_e32 v61, vcc, 0, v45, vcc
	v_add_co_u32_e32 v62, vcc, s71, v46
	s_nop 1
	v_addc_co_u32_e32 v63, vcc, 0, v47, vcc
	global_load_dwordx4 v[64:67], v[44:45], off
	global_load_dwordx4 v[68:71], v[46:47], off
	global_load_dwordx4 v[72:75], v[44:45], off offset:1024
	global_load_dwordx4 v[76:79], v[46:47], off offset:1024
	global_load_dwordx4 v[80:83], v[44:45], off offset:2048
	global_load_dwordx4 v[84:87], v[46:47], off offset:2048
	global_load_dwordx4 v[88:91], v[44:45], off offset:3072
	global_load_dwordx4 v[92:95], v[46:47], off offset:3072
	global_load_dwordx4 v[96:99], v[60:61], off
	global_load_dwordx4 v[100:103], v[62:63], off
	global_load_dwordx4 v[104:107], v[60:61], off offset:1024
	global_load_dwordx4 v[108:111], v[62:63], off offset:1024
	global_load_dwordx4 v[112:115], v[60:61], off offset:2048
	global_load_dwordx4 v[116:119], v[62:63], off offset:2048
	global_load_dwordx4 v[120:123], v[60:61], off offset:3072
	global_load_dwordx4 v[124:127], v[62:63], off offset:3072
	v_pk_mul_f32 v[32:33], v[32:33], v[0:1] op_sel_hi:[1,0]
	v_pk_mul_f32 v[30:31], v[30:31], v[0:1] op_sel_hi:[1,0]
	v_pk_mul_f32 v[28:29], v[28:29], v[0:1] op_sel_hi:[1,0]
	v_pk_mul_f32 v[26:27], v[26:27], v[0:1] op_sel_hi:[1,0]
	v_pk_mul_f32 v[24:25], v[24:25], v[0:1] op_sel_hi:[1,0]
	v_pk_mul_f32 v[22:23], v[22:23], v[0:1] op_sel_hi:[1,0]
	v_pk_mul_f32 v[20:21], v[20:21], v[0:1] op_sel_hi:[1,0]
	v_pk_mul_f32 v[18:19], v[18:19], v[0:1] op_sel_hi:[1,0]
	v_pk_mul_f32 v[16:17], v[16:17], v[0:1] op_sel_hi:[1,0]
	v_pk_mul_f32 v[14:15], v[14:15], v[0:1] op_sel_hi:[1,0]
	v_pk_mul_f32 v[12:13], v[12:13], v[0:1] op_sel_hi:[1,0]
	v_pk_mul_f32 v[10:11], v[10:11], v[0:1] op_sel_hi:[1,0]
	v_pk_mul_f32 v[8:9], v[8:9], v[0:1] op_sel_hi:[1,0]
	v_pk_mul_f32 v[6:7], v[6:7], v[0:1] op_sel_hi:[1,0]
	v_pk_mul_f32 v[4:5], v[4:5], v[0:1] op_sel_hi:[1,0]
	v_pk_mul_f32 v[2:3], v[2:3], v[0:1] op_sel_hi:[1,0]
	s_cmp_eq_u64 s[12:13], 0
	s_waitcnt vmcnt(0)
	v_pk_fma_f32 v[32:33], v[32:33], v[66:67], v[70:71]
	v_pk_fma_f32 v[30:31], v[30:31], v[64:65], v[68:69]
	v_pk_fma_f32 v[28:29], v[28:29], v[74:75], v[78:79]
	v_pk_fma_f32 v[26:27], v[26:27], v[72:73], v[76:77]
	v_pk_fma_f32 v[24:25], v[24:25], v[82:83], v[86:87]
	v_pk_fma_f32 v[22:23], v[22:23], v[80:81], v[84:85]
	v_pk_fma_f32 v[20:21], v[20:21], v[90:91], v[94:95]
	v_pk_fma_f32 v[18:19], v[18:19], v[88:89], v[92:93]
	v_pk_fma_f32 v[16:17], v[16:17], v[98:99], v[102:103]
	v_pk_fma_f32 v[14:15], v[14:15], v[96:97], v[100:101]
	v_pk_fma_f32 v[12:13], v[12:13], v[106:107], v[110:111]
	v_pk_fma_f32 v[10:11], v[10:11], v[104:105], v[108:109]
	v_pk_fma_f32 v[8:9], v[8:9], v[114:115], v[118:119]
	v_pk_fma_f32 v[6:7], v[6:7], v[112:113], v[116:117]
	v_pk_fma_f32 v[4:5], v[4:5], v[122:123], v[126:127]
	v_pk_fma_f32 v[2:3], v[2:3], v[120:121], v[124:125]
	s_cbranch_scc1 .LBB0_1548
	v_lshl_add_u64 v[36:37], v[34:35], 2, s[12:13]
	global_store_dwordx4 v[36:37], v[30:33], off
	global_store_dwordx4 v[36:37], v[26:29], off offset:1024
	global_store_dwordx4 v[36:37], v[22:25], off offset:2048
	global_store_dwordx4 v[36:37], v[18:21], off offset:3072
	v_add_co_u32_e32 v36, vcc, 0x1000, v36
	s_nop 1
	v_addc_co_u32_e32 v37, vcc, 0, v37, vcc
	global_store_dwordx4 v[36:37], v[14:17], off
	global_store_dwordx4 v[36:37], v[10:13], off offset:1024
	global_store_dwordx4 v[36:37], v[6:9], off offset:2048
	global_store_dwordx4 v[36:37], v[2:5], off offset:3072
	s_branch .LBB0_1548

.LBB0_1921:
	s_or_b64 exec, exec, s[4:5]
	s_and_b64 s[4:5], s[18:19], exec
	s_cselect_b32 s5, 0, s13
	s_cselect_b32 s4, 0, s12
	s_lshl_b64 s[10:11], s[68:69], 2
	s_add_u32 s12, s16, s10
	s_addc_u32 s13, s17, s11
	s_add_u32 s10, s14, s10
	v_lshlrev_b64 v[36:37], 2, v[34:35]
	s_addc_u32 s11, s15, s11
	v_lshl_add_u64 v[44:45], s[12:13], 0, v[36:37]
	v_lshl_add_u64 v[46:47], s[10:11], 0, v[36:37]
	v_add_co_u32_e32 v60, vcc, s71, v44
	s_nop 1
	v_addc_co_u32_e32 v61, vcc, 0, v45, vcc
	v_add_co_u32_e32 v62, vcc, s71, v46
	s_nop 1
	v_addc_co_u32_e32 v63, vcc, 0, v47, vcc
	global_load_dwordx4 v[64:67], v[44:45], off
	global_load_dwordx4 v[68:71], v[46:47], off
	global_load_dwordx4 v[72:75], v[44:45], off offset:1024
	global_load_dwordx4 v[76:79], v[46:47], off offset:1024
	global_load_dwordx4 v[80:83], v[44:45], off offset:2048
	global_load_dwordx4 v[84:87], v[46:47], off offset:2048
	global_load_dwordx4 v[88:91], v[44:45], off offset:3072
	global_load_dwordx4 v[92:95], v[46:47], off offset:3072
	global_load_dwordx4 v[96:99], v[60:61], off
	global_load_dwordx4 v[100:103], v[62:63], off
	global_load_dwordx4 v[104:107], v[60:61], off offset:1024
	global_load_dwordx4 v[108:111], v[62:63], off offset:1024
	global_load_dwordx4 v[112:115], v[60:61], off offset:2048
	global_load_dwordx4 v[116:119], v[62:63], off offset:2048
	global_load_dwordx4 v[120:123], v[60:61], off offset:3072
	global_load_dwordx4 v[124:127], v[62:63], off offset:3072
	v_pk_mul_f32 v[32:33], v[32:33], v[0:1] op_sel_hi:[1,0]
	v_pk_mul_f32 v[30:31], v[30:31], v[0:1] op_sel_hi:[1,0]
	v_pk_mul_f32 v[28:29], v[28:29], v[0:1] op_sel_hi:[1,0]
	v_pk_mul_f32 v[26:27], v[26:27], v[0:1] op_sel_hi:[1,0]
	v_pk_mul_f32 v[24:25], v[24:25], v[0:1] op_sel_hi:[1,0]
	v_pk_mul_f32 v[22:23], v[22:23], v[0:1] op_sel_hi:[1,0]
	v_pk_mul_f32 v[20:21], v[20:21], v[0:1] op_sel_hi:[1,0]
	v_pk_mul_f32 v[18:19], v[18:19], v[0:1] op_sel_hi:[1,0]
	v_pk_mul_f32 v[16:17], v[16:17], v[0:1] op_sel_hi:[1,0]
	v_pk_mul_f32 v[14:15], v[14:15], v[0:1] op_sel_hi:[1,0]
	v_pk_mul_f32 v[12:13], v[12:13], v[0:1] op_sel_hi:[1,0]
	v_pk_mul_f32 v[10:11], v[10:11], v[0:1] op_sel_hi:[1,0]
	v_pk_mul_f32 v[8:9], v[8:9], v[0:1] op_sel_hi:[1,0]
	v_pk_mul_f32 v[6:7], v[6:7], v[0:1] op_sel_hi:[1,0]
	v_pk_mul_f32 v[4:5], v[4:5], v[0:1] op_sel_hi:[1,0]
	v_pk_mul_f32 v[2:3], v[2:3], v[0:1] op_sel_hi:[1,0]
	s_cmp_eq_u64 s[4:5], 0
	s_waitcnt vmcnt(0)
	v_pk_fma_f32 v[32:33], v[32:33], v[66:67], v[70:71]
	v_pk_fma_f32 v[30:31], v[30:31], v[64:65], v[68:69]
	v_pk_fma_f32 v[28:29], v[28:29], v[74:75], v[78:79]
	v_pk_fma_f32 v[26:27], v[26:27], v[72:73], v[76:77]
	v_pk_fma_f32 v[24:25], v[24:25], v[82:83], v[86:87]
	v_pk_fma_f32 v[22:23], v[22:23], v[80:81], v[84:85]
	v_pk_fma_f32 v[20:21], v[20:21], v[90:91], v[94:95]
	v_pk_fma_f32 v[18:19], v[18:19], v[88:89], v[92:93]
	v_pk_fma_f32 v[16:17], v[16:17], v[98:99], v[102:103]
	v_pk_fma_f32 v[14:15], v[14:15], v[96:97], v[100:101]
	v_pk_fma_f32 v[12:13], v[12:13], v[106:107], v[110:111]
	v_pk_fma_f32 v[10:11], v[10:11], v[104:105], v[108:109]
	v_pk_fma_f32 v[8:9], v[8:9], v[114:115], v[118:119]
	v_pk_fma_f32 v[6:7], v[6:7], v[112:113], v[116:117]
	v_pk_fma_f32 v[4:5], v[4:5], v[122:123], v[126:127]
	v_pk_fma_f32 v[2:3], v[2:3], v[120:121], v[124:125]
	s_cbranch_scc1 .LBB0_1923
	v_lshl_add_u64 v[36:37], v[34:35], 2, s[4:5]
	global_store_dwordx4 v[36:37], v[30:33], off
	global_store_dwordx4 v[36:37], v[26:29], off offset:1024
	global_store_dwordx4 v[36:37], v[22:25], off offset:2048
	global_store_dwordx4 v[36:37], v[18:21], off offset:3072
	v_add_co_u32_e32 v36, vcc, 0x1000, v36
	s_nop 1
	v_addc_co_u32_e32 v37, vcc, 0, v37, vcc
	global_store_dwordx4 v[36:37], v[14:17], off
	global_store_dwordx4 v[36:37], v[10:13], off offset:1024
	global_store_dwordx4 v[36:37], v[6:9], off offset:2048
	global_store_dwordx4 v[36:37], v[2:5], off offset:3072
